# P11: scalar compare in candidate bisection, DPP softmax, batched ballot compares in top-k bisection
# speedup vs baseline: 1.0335x; 1.0076x over previous
; DEVI void phase11(const Params& P, int l, int pass, char* smem) {
;     ...
;       for (int b = 31; b >= KLOW; --b) {
; #pragma unroll
;         for (int li = 0; li < 4; ++li) {
;           unsigned cand = T[li] | (1u << b);
;           int cnt = __popcll(__ballot(k0[li] >= cand)) + __popcll(__ballot(k1[li] >= cand));
;           if (cnt >= 16) T[li] = cand;
;         }
;       }
; #pragma unroll
;       for (int li = 0; li < 4; ++li) {
;         const int Lx = w * 4 + li;
;         const unsigned T2 = T[li] + (1u << KLOW);
;         bool g0 = k0[li] >= T2, g1 = k1[li] >= T2;
;         bool q0 = (k0[li] >= T[li]) && !g0, q1 = (k1[li] >= T[li]) && !g1;
;         unsigned long long mg0 = __ballot(g0), mg1 = __ballot(g1), mq0 = __ballot(q0), mq1 = __ballot(q1);
;         int ng0 = __popcll(mg0), ng = ng0 + __popcll(mg1);
;         int p0 = g0 ? __popcll(mg0 & ltmask) : ng + __popcll(mq0 & ltmask);
;         int p1 = g1 ? ng0 + __popcll(mg1 & ltmask) : ng + __popcll(mq0) + __popcll(mq1 & ltmask);
;         if ((g0 || q0) && p0 < 16) { sv[Lx * 16 + p0] = v0[li]; si[Lx * 16 + p0] = lane; }
;         if ((g1 || q1) && p1 < 16) { sv[Lx * 16 + p1] = v1[li]; si[Lx * 16 + p1] = lane + 64; }
.LBB0_138:
	s_lshl_b32 s55, 1, s54
	s_or_b32 s56, s55, s62
	s_or_b32 s57, s55, s84
	v_cmp_le_u32_e64 s[60:61], s56, v15
	v_cmp_le_u32_e64 s[64:65], s56, v14
	v_cmp_le_u32_e64 s[66:67], s57, v13
	v_cmp_le_u32_e64 s[80:81], s57, v12
	s_or_b32 s58, s55, s24
	s_or_b32 s59, s55, s75
	s_bcnt1_i32_b64 s85, s[60:61]
	s_bcnt1_i32_b64 s88, s[64:65]
	v_cmp_le_u32_e64 s[60:61], s58, v9
	v_cmp_le_u32_e64 s[64:65], s58, v8
	s_add_i32 s85, s85, s88
	s_cmp_gt_u32 s85, 15
	s_cselect_b32 s62, s56, s62
	s_bcnt1_i32_b64 s85, s[66:67]
	s_bcnt1_i32_b64 s88, s[80:81]
	v_cmp_le_u32_e64 s[66:67], s59, v5
	v_cmp_le_u32_e64 s[80:81], s59, v4
	s_add_i32 s85, s85, s88
	s_cmp_gt_u32 s85, 15
	s_cselect_b32 s84, s57, s84
	s_bcnt1_i32_b64 s85, s[60:61]
	s_bcnt1_i32_b64 s88, s[64:65]
	s_add_i32 s85, s85, s88
	s_cmp_gt_u32 s85, 15
	s_cselect_b32 s24, s58, s24
	s_bcnt1_i32_b64 s85, s[66:67]
	s_bcnt1_i32_b64 s88, s[80:81]
	s_add_i32 s85, s85, s88
	s_cmp_gt_u32 s85, 15
	s_cselect_b32 s75, s59, s75
	s_add_i32 s54, s54, -1
	s_cmp_gt_u32 s54, 11
	s_cbranch_scc1 .LBB0_138
	s_add_i32 s54, s62, 0x1000
	v_cmp_gt_u32_e64 s[66:67], s54, v15
	v_cmp_le_u32_e64 s[58:59], s62, v15
	v_cmp_le_u32_e32 vcc, s54, v14
	v_cmp_le_u32_e64 s[56:57], s54, v15
	v_cmp_gt_u32_e64 s[60:61], s54, v14
	v_cmp_le_u32_e64 s[54:55], s62, v14
	s_and_b64 s[62:63], s[58:59], s[66:67]
	v_cndmask_b32_e64 v14, 0, 1, s[62:63]
	s_and_b64 s[64:65], s[54:55], s[60:61]
	v_cmp_ne_u32_e64 s[62:63], 0, v14
	v_cndmask_b32_e64 v14, 0, 1, s[64:65]
	s_bcnt1_i32_b64 s85, s[56:57]
	s_bcnt1_i32_b64 s88, vcc
	v_cmp_ne_u32_e64 s[64:65], 0, v14
	s_add_i32 s88, s88, s85
	s_and_saveexec_b64 s[80:81], s[66:67]
	s_xor_b64 s[66:67], exec, s[80:81]
	s_cbranch_execz .LBB0_141
	v_and_b32_e32 v15, s62, v100
	v_and_b32_e32 v14, s63, v91
	v_bcnt_u32_b32 v15, v15, 0
	v_bcnt_u32_b32 v14, v14, v15
	v_add_u32_e32 v14, s88, v14
	s_andn2_saveexec_b64 s[66:67], s[66:67]
	s_branch .LBB0_142

; DEVI void phase11(const Params& P, int l, int pass, char* smem) {
;     ...
;     {
;       float cv[2]; unsigned ck[2], T[2]; int ce[2];
;       const int cij = (lane < 50) ? (int)CAND_IJ[lane] : 0;
;       const int ci = cij >> 4, cj = cij & 15;
; #pragma unroll
;       for (int hi = 0; hi < 2; ++hi) {
;         const int h = w * 2 + hi;
;         T[hi] = 0;
;         cv[hi] = svs[(2 * h) * 16 + ci] + svs[(2 * h + 1) * 16 + cj];
;         ce[hi] = sis[(2 * h) * 16 + ci] * 128 + sis[(2 * h + 1) * 16 + cj];
;         ck[hi] = (lane < 50) ? fkey(cv[hi]) : 0u;
;       }
;       for (int b = 31; b >= KLOW; --b) {
; #pragma unroll
;         for (int hi = 0; hi < 2; ++hi) {
;           unsigned cand = T[hi] | (1u << b);
;           int cnt = __popcll(__ballot(ck[hi] >= cand));
;           if (cnt >= 16) T[hi] = cand;
;         }
;       }
.LBB0_247:
	s_or_b64 exec, exec, s[54:55]
	v_or_b32_e32 v1, v7, v121
	v_add3_u32 v1, v1, v6, v9
	v_add3_u32 v1, v1, v8, v11
	v_add3_u32 v1, v1, v10, v13
	v_add3_u32 v1, v1, v12, v15
	v_cmp_gt_f32_e32 vcc, v3, v4
	v_add3_u32 v1, v1, v14, v17
	s_nop 0
	v_addc_co_u32_e32 v1, vcc, v1, v16, vcc
	v_add3_u32 v1, v1, v19, v18
	v_add_lshl_u32 v0, v1, v0, 2
	ds_write2st64_b32 v0, v4, v5 offset0:46 offset1:50
	v_mov_b32_e32 v0, v233
	v_lshrrev_b32_e32 v1, 4, v0
	v_or_b32_e32 v1, v1, v109
	v_lshlrev_b32_e32 v1, 2, v1
	v_add_u32_e32 v2, 0x2c00, v1
	v_and_or_b32 v0, v0, 15, v109
	ds_read2_b32 v[4:5], v2 offset0:128 offset1:160
	v_lshlrev_b32_e32 v2, 2, v0
	v_add_u32_e32 v0, 0x2c00, v2
	ds_read2_b32 v[6:7], v0 offset0:144 offset1:176
	v_add_u32_e32 v0, 0x3000, v1
	s_waitcnt lgkmcnt(1)
	v_mov_b32_e32 v8, v5
	v_mov_b32_e32 v9, v4
	v_add_u32_e32 v2, 0x3000, v2
	s_waitcnt lgkmcnt(0)
	v_mov_b32_e32 v4, v7
	v_mov_b32_e32 v5, v6
	v_pk_add_f32 v[4:5], v[8:9], v[4:5]
	ds_read2_b32 v[0:1], v0 offset0:128 offset1:160
	v_not_b32_e32 v6, v5
	v_or_b32_e32 v7, 0x80000000, v5
	v_cmp_gt_i32_e32 vcc, 0, v5
	v_or_b32_e32 v8, 0x80000000, v4
	ds_read2_b32 v[2:3], v2 offset0:144 offset1:176
	v_cndmask_b32_e32 v6, v7, v6, vcc
	v_cndmask_b32_e64 v7, 0, v6, s[40:41]
	v_not_b32_e32 v6, v4
	v_cmp_gt_i32_e32 vcc, 0, v4
	s_nop 1
	v_cndmask_b32_e32 v6, v8, v6, vcc
	v_cmp_gt_i32_e32 vcc, 0, v7
	s_bcnt1_i32_b64 s24, vcc
	v_cndmask_b32_e64 v6, 0, v6, s[40:41]
	s_cmp_gt_u32 s24, 15
	v_cmp_gt_i32_e32 vcc, 0, v6
	s_cselect_b32 s56, 0x80000000, 0
	s_bcnt1_i32_b64 s24, vcc
	s_cmp_gt_u32 s24, 15
	s_cselect_b32 s57, 0x80000000, 0
	s_or_b32 s58, s56, 2.0
	v_cmp_le_u32_e32 vcc, s58, v7
	s_bcnt1_i32_b64 s24, vcc
	s_cmp_gt_u32 s24, 15
	s_cselect_b32 s56, s58, s56
	s_or_b32 s58, s57, 2.0
	v_cmp_le_u32_e32 vcc, s58, v6
	s_bcnt1_i32_b64 s24, vcc
	s_cmp_gt_u32 s24, 15
	s_cselect_b32 s57, s58, s57
	s_or_b32 s58, s56, 0x20000000
	v_cmp_le_u32_e32 vcc, s58, v7
	s_bcnt1_i32_b64 s24, vcc
	s_cmp_gt_u32 s24, 15
	s_cselect_b32 s56, s58, s56
	s_or_b32 s58, s57, 0x20000000
	v_cmp_le_u32_e32 vcc, s58, v6
	s_bcnt1_i32_b64 s24, vcc
	s_cmp_gt_u32 s24, 15
	s_cselect_b32 s57, s58, s57
	s_or_b32 s58, s56, 0x10000000
	v_cmp_le_u32_e32 vcc, s58, v7
	s_bcnt1_i32_b64 s24, vcc
	s_cmp_gt_u32 s24, 15
	s_cselect_b32 s56, s58, s56
	s_or_b32 s58, s57, 0x10000000
	v_cmp_le_u32_e32 vcc, s58, v6
	s_bcnt1_i32_b64 s24, vcc
	s_cmp_gt_u32 s24, 15
	s_cselect_b32 s57, s58, s57
	s_or_b32 s58, s56, 0x8000000
	v_cmp_le_u32_e32 vcc, s58, v7
	s_bcnt1_i32_b64 s24, vcc
	s_cmp_gt_u32 s24, 15
	s_cselect_b32 s56, s58, s56
	s_or_b32 s58, s57, 0x8000000
	v_cmp_le_u32_e32 vcc, s58, v6
	s_bcnt1_i32_b64 s24, vcc
	s_cmp_gt_u32 s24, 15
	s_cselect_b32 s57, s58, s57
	s_or_b32 s58, s56, 0x4000000
	v_cmp_le_u32_e32 vcc, s58, v7
	s_bcnt1_i32_b64 s24, vcc
	s_cmp_gt_u32 s24, 15
	s_cselect_b32 s56, s58, s56
	s_or_b32 s58, s57, 0x4000000
	v_cmp_le_u32_e32 vcc, s58, v6
	s_bcnt1_i32_b64 s24, vcc
	s_cmp_gt_u32 s24, 15
	s_cselect_b32 s57, s58, s57
	s_or_b32 s58, s56, 0x2000000
	v_cmp_le_u32_e32 vcc, s58, v7
	s_bcnt1_i32_b64 s24, vcc
	s_cmp_gt_u32 s24, 15
	s_cselect_b32 s56, s58, s56
	s_or_b32 s58, s57, 0x2000000
	v_cmp_le_u32_e32 vcc, s58, v6
	s_bcnt1_i32_b64 s24, vcc
	s_cmp_gt_u32 s24, 15
	s_cselect_b32 s57, s58, s57
	s_or_b32 s58, s56, 0x1000000
	v_cmp_le_u32_e32 vcc, s58, v7
	s_bcnt1_i32_b64 s24, vcc
	s_cmp_gt_u32 s24, 15
	s_cselect_b32 s56, s58, s56
	s_or_b32 s58, s57, 0x1000000
	v_cmp_le_u32_e32 vcc, s58, v6
	s_bcnt1_i32_b64 s24, vcc
	s_cmp_gt_u32 s24, 15
	s_cselect_b32 s57, s58, s57
	s_or_b32 s58, s56, 0x800000
	v_cmp_le_u32_e32 vcc, s58, v7
	s_bcnt1_i32_b64 s24, vcc
	s_cmp_gt_u32 s24, 15
	s_cselect_b32 s56, s58, s56
	s_or_b32 s58, s57, 0x800000
	v_cmp_le_u32_e32 vcc, s58, v6
	s_bcnt1_i32_b64 s24, vcc
	s_cmp_gt_u32 s24, 15
	s_cselect_b32 s57, s58, s57
	s_or_b32 s58, s56, 0x400000
	v_cmp_le_u32_e32 vcc, s58, v7
	s_bcnt1_i32_b64 s24, vcc
	s_cmp_gt_u32 s24, 15
	s_cselect_b32 s56, s58, s56
	s_or_b32 s58, s57, 0x400000
	v_cmp_le_u32_e32 vcc, s58, v6
	s_bcnt1_i32_b64 s24, vcc
	s_cmp_gt_u32 s24, 15
	s_cselect_b32 s57, s58, s57
	s_or_b32 s58, s56, 0x200000
	v_cmp_le_u32_e32 vcc, s58, v7
	s_bcnt1_i32_b64 s24, vcc
	s_cmp_gt_u32 s24, 15
	s_cselect_b32 s56, s58, s56
	s_or_b32 s58, s57, 0x200000
; DEVI void phase11(const Params& P, int l, int pass, char* smem) {
;     ...
;       for (int b = 31; b >= KLOW; --b) {
; #pragma unroll
;         for (int hi = 0; hi < 2; ++hi) {
;           unsigned cand = T[hi] | (1u << b);
;           int cnt = __popcll(__ballot(ck[hi] >= cand));
;           if (cnt >= 16) T[hi] = cand;
;         }
;       }
; #pragma unroll
;       for (int hi = 0; hi < 2; ++hi) {
;         const int h = w * 2 + hi;
;         const unsigned T2 = T[hi] + (1u << KLOW);
;         bool g = ck[hi] >= T2, q = (ck[hi] >= T[hi]) && !g && (lane < 50);
;         unsigned long long mg = __ballot(g), mq = __ballot(q);
;         int p = g ? __popcll(mg & ltmask) : __popcll(mg) + __popcll(mq & ltmask);
;         if ((g || q) && p < 16) { tops[h * 16 + p] = cv[hi]; tope[h * 16 + p] = ce[hi]; }
;       }
;     }
	v_cmp_le_u32_e32 vcc, s58, v6
	s_bcnt1_i32_b64 s24, vcc
	s_cmp_gt_u32 s24, 15
	s_cselect_b32 s57, s58, s57
	s_or_b32 s58, s56, 0x100000
	v_cmp_le_u32_e32 vcc, s58, v7
	s_bcnt1_i32_b64 s24, vcc
	s_cmp_gt_u32 s24, 15
	s_cselect_b32 s56, s58, s56
	s_or_b32 s58, s57, 0x100000
	v_cmp_le_u32_e32 vcc, s58, v6
	s_bcnt1_i32_b64 s24, vcc
	s_cmp_gt_u32 s24, 15
	s_cselect_b32 s57, s58, s57
	s_or_b32 s58, s56, 0x80000
	v_cmp_le_u32_e32 vcc, s58, v7
	s_bcnt1_i32_b64 s24, vcc
	s_cmp_gt_u32 s24, 15
	s_cselect_b32 s56, s58, s56
	s_or_b32 s58, s57, 0x80000
	v_cmp_le_u32_e32 vcc, s58, v6
	s_bcnt1_i32_b64 s24, vcc
	s_cmp_gt_u32 s24, 15
	s_cselect_b32 s57, s58, s57
	s_or_b32 s58, s56, 0x40000
	v_cmp_le_u32_e32 vcc, s58, v7
	s_bcnt1_i32_b64 s24, vcc
	s_cmp_gt_u32 s24, 15
	s_cselect_b32 s56, s58, s56
	s_or_b32 s58, s57, 0x40000
	v_cmp_le_u32_e32 vcc, s58, v6
	s_bcnt1_i32_b64 s24, vcc
	s_cmp_gt_u32 s24, 15
	s_cselect_b32 s57, s58, s57
	s_or_b32 s58, s56, 0x20000
	v_cmp_le_u32_e32 vcc, s58, v7
	s_bcnt1_i32_b64 s24, vcc
	s_cmp_gt_u32 s24, 15
	s_cselect_b32 s56, s58, s56
	s_or_b32 s58, s57, 0x20000
	v_cmp_le_u32_e32 vcc, s58, v6
	s_bcnt1_i32_b64 s24, vcc
	s_cmp_gt_u32 s24, 15
	s_cselect_b32 s57, s58, s57
	s_or_b32 s58, s56, 0x10000
	v_cmp_le_u32_e32 vcc, s58, v7
	s_bcnt1_i32_b64 s24, vcc
	s_cmp_gt_u32 s24, 15
	s_cselect_b32 s56, s58, s56
	s_or_b32 s58, s57, 0x10000
	v_cmp_le_u32_e32 vcc, s58, v6
	s_bcnt1_i32_b64 s24, vcc
	s_cmp_gt_u32 s24, 15
	s_cselect_b32 s57, s58, s57
	s_or_b32 s58, s56, 0x8000
	v_cmp_le_u32_e32 vcc, s58, v7
	s_bcnt1_i32_b64 s24, vcc
	s_cmp_gt_u32 s24, 15
	s_cselect_b32 s56, s58, s56
	s_or_b32 s58, s57, 0x8000
	v_cmp_le_u32_e32 vcc, s58, v6
	s_bcnt1_i32_b64 s24, vcc
	s_cmp_gt_u32 s24, 15
	s_cselect_b32 s57, s58, s57
	s_or_b32 s58, s56, 0x4000
	v_cmp_le_u32_e32 vcc, s58, v7
	s_bcnt1_i32_b64 s24, vcc
	s_cmp_gt_u32 s24, 15
	s_cselect_b32 s56, s58, s56
	s_or_b32 s58, s57, 0x4000
	v_cmp_le_u32_e32 vcc, s58, v6
	s_bcnt1_i32_b64 s24, vcc
	s_cmp_gt_u32 s24, 15
	s_cselect_b32 s57, s58, s57
	s_or_b32 s58, s56, 0x2000
	v_cmp_le_u32_e32 vcc, s58, v7
	s_bcnt1_i32_b64 s24, vcc
	s_cmp_gt_u32 s24, 15
	s_cselect_b32 s56, s58, s56
	s_or_b32 s58, s57, 0x2000
	v_cmp_le_u32_e32 vcc, s58, v6
	s_bcnt1_i32_b64 s24, vcc
	s_cmp_gt_u32 s24, 15
	s_cselect_b32 s62, s58, s57
	s_or_b32 s57, s56, 0x1000
	v_cmp_le_u32_e32 vcc, s57, v7
	s_bcnt1_i32_b64 s24, vcc
	s_cmp_gt_u32 s24, 15
	s_cselect_b32 s24, s57, s56
	s_add_i32 s56, s24, 0x1000
	v_cmp_le_u32_e64 s[54:55], s56, v7
	v_cmp_gt_u32_e64 s[58:59], s56, v7
	v_cmp_le_u32_e64 s[56:57], s24, v7
	s_and_b64 s[56:57], s[56:57], s[58:59]
	s_and_b64 s[60:61], s[40:41], s[56:57]
	s_or_b32 s63, s62, 0x1000
	v_cndmask_b32_e64 v7, 0, 1, s[60:61]
	v_cmp_le_u32_e32 vcc, s63, v6
	v_cmp_ne_u32_e64 s[56:57], 0, v7
	s_and_saveexec_b64 s[64:65], s[58:59]
	s_xor_b64 s[58:59], exec, s[64:65]
	v_and_b32_e32 v8, s56, v100
	v_and_b32_e32 v7, s57, v91
	v_bcnt_u32_b32 v8, v8, 0
	s_bcnt1_i32_b64 s24, s[54:55]
	v_bcnt_u32_b32 v7, v7, v8
	v_add_u32_e32 v7, s24, v7
	s_andn2_saveexec_b64 s[56:57], s[58:59]
	v_and_b32_e32 v8, s54, v100
	v_and_b32_e32 v7, s55, v91
	v_bcnt_u32_b32 v8, v8, 0
	v_bcnt_u32_b32 v7, v7, v8
	s_or_b64 exec, exec, s[56:57]
	s_or_b64 s[56:57], s[54:55], s[60:61]
	v_cmp_gt_u32_e64 s[54:55], 16, v7
	s_and_b64 s[56:57], s[56:57], s[54:55]
	s_and_saveexec_b64 s[54:55], s[56:57]
	s_cbranch_execz .LBB0_255
	s_waitcnt lgkmcnt(0)
	v_lshl_add_u32 v0, v0, 7, v2
	v_or_b32_e32 v2, v7, v124
	v_lshlrev_b32_e32 v2, 2, v2
	ds_write2st64_b32 v2, v5, v0 offset0:40 offset1:42
.LBB0_255:
	s_or_b64 exec, exec, s[54:55]
	s_bcnt1_i32_b64 s24, vcc
	s_cmp_gt_u32 s24, 15
	s_cselect_b32 s24, s63, s62
	s_add_i32 s54, s24, 0x1000
	v_cmp_le_u32_e32 vcc, s54, v6
	v_cmp_gt_u32_e64 s[56:57], s54, v6
	v_cmp_le_u32_e64 s[54:55], s24, v6
	s_and_b64 s[54:55], s[54:55], s[56:57]
	s_and_b64 s[58:59], s[40:41], s[54:55]
	s_waitcnt lgkmcnt(1)
	v_cndmask_b32_e64 v0, 0, 1, s[58:59]
	v_cmp_ne_u32_e64 s[54:55], 0, v0
	s_and_saveexec_b64 s[60:61], s[56:57]
	s_xor_b64 s[56:57], exec, s[60:61]
	s_cbranch_execz .LBB0_257
	s_waitcnt lgkmcnt(0)
	v_and_b32_e32 v2, s54, v100
	v_and_b32_e32 v0, s55, v91
	v_bcnt_u32_b32 v2, v2, 0
	s_bcnt1_i32_b64 s24, vcc
	v_bcnt_u32_b32 v0, v0, v2
	v_add_u32_e32 v0, s24, v0

; DEVI void phase11(const Params& P, int l, int pass, char* smem) {
;     ...
;     if (tid < 128) {
;       float s = tops[tid];
;       float mx = s;
;       mx = fmaxf(mx, __shfl_xor(mx, 1)); mx = fmaxf(mx, __shfl_xor(mx, 2));
;       mx = fmaxf(mx, __shfl_xor(mx, 4)); mx = fmaxf(mx, __shfl_xor(mx, 8));
;       float e = __expf(s - mx);
;       float sm = e;
;       sm += __shfl_xor(sm, 1); sm += __shfl_xor(sm, 2); sm += __shfl_xor(sm, 4); sm += __shfl_xor(sm, 8);
;       tops[tid] = e / sm;
;     }
.LBB0_261:
	s_or_b64 exec, exec, s[54:55]
	s_waitcnt lgkmcnt(0)
	s_and_saveexec_b64 s[54:55], s[42:43]
	s_cbranch_execz .LBB0_263
	v_sub_u32_e32 v8, v122, v108
	ds_read_b32 v0, v8 offset:10240
	s_waitcnt lgkmcnt(0)
	v_max_f32_e32 v2, v0, v0
	s_nop 1
	v_max_f32_dpp v1, v2, v2 quad_perm:[1,0,3,2] row_mask:0xf bank_mask:0xf
	s_nop 1
	v_max_f32_dpp v2, v1, v1 quad_perm:[2,3,0,1] row_mask:0xf bank_mask:0xf
	s_nop 1
	v_max_f32_dpp v1, v2, v2 row_shl:4 row_mask:0xf bank_mask:0x5
	v_max_f32_dpp v1, v2, v2 row_shr:4 row_mask:0xf bank_mask:0xa
	s_nop 1
	v_max_f32_dpp v2, v1, v1 row_ror:8 row_mask:0xf bank_mask:0xf
	s_nop 0
	v_sub_f32_e32 v0, v0, v2
	v_mul_f32_e32 v0, 0x3fb8aa3b, v0
	v_exp_f32_e32 v0, v0
	s_nop 1
	v_add_f32_dpp v1, v0, v0 quad_perm:[1,0,3,2] row_mask:0xf bank_mask:0xf
	s_nop 1
	v_add_f32_dpp v2, v1, v1 quad_perm:[2,3,0,1] row_mask:0xf bank_mask:0xf
	s_nop 1
	v_add_f32_dpp v3, v2, v2 row_shl:4 row_mask:0xf bank_mask:0x5
	v_add_f32_dpp v3, v2, v2 row_shr:4 row_mask:0xf bank_mask:0xa
	s_nop 1
	v_add_f32_dpp v1, v3, v3 row_ror:8 row_mask:0xf bank_mask:0xf
	s_nop 0
	v_div_scale_f32 v2, s[56:57], v1, v1, v0
	v_rcp_f32_e32 v3, v2
	v_div_scale_f32 v4, vcc, v0, v1, v0
	v_fma_f32 v5, -v2, v3, 1.0
	v_fmac_f32_e32 v3, v5, v3
	v_mul_f32_e32 v5, v4, v3
	v_fma_f32 v6, -v2, v5, v4
	v_fmac_f32_e32 v5, v6, v3
	v_fma_f32 v2, -v2, v5, v4
	v_div_fmas_f32 v2, v2, v3, v5
	v_div_fixup_f32 v0, v2, v1, v0
	ds_write_b32 v8, v0 offset:10240
